# hand-written EpiFfn epilogue fast path (DPP-fused conv FMACs, SoA channels) for pm!=64 tiles in the up-gate GEMM
# baseline (speedup 1.0000x reference)
;     __device__ __forceinline__ void operator()(const f32x4 (&acc)[2][2][4][2], const Unit& u, int wr, int wc, int fr, int fq) const {
;         const int ch0 = u.pn * 128 + wc * 32 + 8 * fq;
;         float w0[8], w1[8], w2[8], bb[8]; load8f(cw + ch0, w0); load8f(cw + DFF + ch0, w1); load8f(cw + 2 * DFF + ch0, w2); load8f(cb + ch0, bb);
;         const int rbase = u.pm * BM + wr * 64 + fr;
;         const int b0 = (u.pm * BM) / TP, rb = (b0 + 1) * TP;
; #pragma unroll
;         for (int ai = 0; ai < 2; ++ai) {
;             if (u.pm == 64 && ai == 1) {
; #pragma unroll
;                 for (int m = 0; m < 4; ++m) { const int r = rbase + HALF + 16 * m, sb = r - MP;
;                     float u2[8], u1[8], o[8], uu[8]; load8f(st + (size_t)(sb * 2) * DFF + ch0, u2); load8f(st + (size_t)(sb * 2 + 1) * DFF + ch0, u1);
; #pragma unroll
;                     for (int k = 0; k < 8; ++k) { const float x = acc[1][0][m][k >> 2][k & 3], g = acc[1][1][m][k >> 2][k & 3]; uu[k] = x;
;                         const float uc = w0[k] * u2[k] + w1[k] * u1[k] + w2[k] * x + bb[k]; o[k] = uc * sigmoidf_(uc) * g; }
;                     *(u32x4*)(ACT + (size_t)r * DFF + ch0) = pack8(o);
;                     store8f(outs + (size_t)(sb * 2) * DFF + ch0, u1); store8f(outs + (size_t)(sb * 2 + 1) * DFF + ch0, uu); }
;             } else {
; #pragma unroll
;                 for (int m = 0; m < 4; ++m) { const int r = rbase + ai * HALF + 16 * m; const bool hi = r >= rb; const int t = hi ? r - rb : r - b0 * TP, b = hi ? b0 + 1 : b0;
;                     float o[8], uu[8], gg[8];
; #pragma unroll
;                     for (int k = 0; k < 8; ++k) { const float x = acc[ai][0][m][k >> 2][k & 3], g = acc[ai][1][m][k >> 2][k & 3]; uu[k] = x; gg[k] = g;
;                         float u1 = dpp_ror1(x), u2 = dpp_ror2(x);
;                         if (m > 0) { const float xp = acc[ai][0][m > 0 ? m - 1 : 0][k >> 2][k & 3]; const float p1 = dpp_ror1(xp), p2 = dpp_ror2(xp); u1 = fr >= 1 ? u1 : p1; u2 = fr >= 2 ? u2 : p2; }
;                         if (t == 0) u1 = 0.f; if (t <= 1) u2 = 0.f;
;                         const float uc = w0[k] * u2 + w1[k] * u1 + w2[k] * x + bb[k]; o[k] = uc * sigmoidf_(uc) * g; }
;                     if (m > 0 || fr >= 2) *(u32x4*)(ACT + (size_t)r * DFF + ch0) = pack8(o);
.LBB0_883:
	s_cmp_lg_u32 s90, 64
	s_cbranch_scc0 .Lp8e_orig
	v_lshl_or_b32 v174, s10, 7, v181
	v_lshlrev_b32_e32 v176, 2, v174
	s_lshl_b32 s91, s90, 8
	global_load_dwordx4 v[50:53], v176, s[66:67]
	global_load_dwordx4 v[54:57], v176, s[66:67] offset:16
	global_load_dwordx4 v[58:61], v176, s[78:79]
	global_load_dwordx4 v[62:65], v176, s[78:79] offset:16
	global_load_dwordx4 v[66:69], v176, s[80:81]
	global_load_dwordx4 v[70:73], v176, s[80:81] offset:16
	global_load_dwordx4 v[74:77], v176, s[68:69]
	global_load_dwordx4 v[78:81], v176, s[68:69] offset:16
	s_mul_hi_u32 s35, s91, 0xfe03f81
	s_lshr_b32 s35, s35, 7
	s_add_i32 s54, s35, 1
	s_mul_i32 s85, s54, 0x810
	s_add_i32 s91, s91, s18
	v_mul_u32_u24_e32 v183, s22, v178
	v_lshl_add_u32 v183, v174, 1, v183
	v_mul_u32_u24_e32 v236, s39, v178
	v_lshl_add_u32 v236, v174, 1, v236
	v_add_u32_e32 v237, s22, v236
	v_mul_i32_i24_e32 v238, s22, v180
	v_lshl_add_u32 v238, v174, 1, v238
	v_mul_i32_i24_e32 v239, s39, v180
	v_lshl_add_u32 v239, v174, 2, v239
	s_waitcnt vmcnt(0)
	s_add_i32 s55, s91, 0
	s_cmp_ge_i32 s55, s85
	s_cselect_b32 s83, s54, s35
	s_mul_i32 s32, s83, 0x810
	s_sub_i32 s32, s55, s32
	s_mul_i32 s10, s55, 0x1600
	s_add_u32 s92, s60, s10
	s_addc_u32 s93, s61, 0
	v_fma_f32 v184, v66, v150, v74
	v_fma_f32 v185, v67, v151, v75
	v_fma_f32 v186, v68, v152, v76
	v_fma_f32 v187, v69, v153, v77
	v_fma_f32 v188, v70, v142, v78
	v_fma_f32 v189, v71, v143, v79
	v_fma_f32 v190, v72, v144, v80
	v_fma_f32 v191, v73, v145, v81
	v_fmac_f32_dpp v184, v150, v58 row_shr:1 row_mask:0xf bank_mask:0xf
	v_fmac_f32_dpp v185, v151, v59 row_shr:1 row_mask:0xf bank_mask:0xf
	v_fmac_f32_dpp v186, v152, v60 row_shr:1 row_mask:0xf bank_mask:0xf
	v_fmac_f32_dpp v187, v153, v61 row_shr:1 row_mask:0xf bank_mask:0xf
	v_fmac_f32_dpp v188, v142, v62 row_shr:1 row_mask:0xf bank_mask:0xf
	v_fmac_f32_dpp v189, v143, v63 row_shr:1 row_mask:0xf bank_mask:0xf
	v_fmac_f32_dpp v190, v144, v64 row_shr:1 row_mask:0xf bank_mask:0xf
	v_fmac_f32_dpp v191, v145, v65 row_shr:1 row_mask:0xf bank_mask:0xf
	v_fmac_f32_dpp v184, v150, v50 row_shr:2 row_mask:0xf bank_mask:0xf
	v_fmac_f32_dpp v185, v151, v51 row_shr:2 row_mask:0xf bank_mask:0xf
	v_fmac_f32_dpp v186, v152, v52 row_shr:2 row_mask:0xf bank_mask:0xf
	v_fmac_f32_dpp v187, v153, v53 row_shr:2 row_mask:0xf bank_mask:0xf
	v_fmac_f32_dpp v188, v142, v54 row_shr:2 row_mask:0xf bank_mask:0xf
	v_fmac_f32_dpp v189, v143, v55 row_shr:2 row_mask:0xf bank_mask:0xf
	v_fmac_f32_dpp v190, v144, v56 row_shr:2 row_mask:0xf bank_mask:0xf
	v_fmac_f32_dpp v191, v145, v57 row_shr:2 row_mask:0xf bank_mask:0xf
	v_mul_f32_e32 v192, 0xbfb8aa3b, v184
	v_mul_f32_e32 v193, 0xbfb8aa3b, v185
	v_mul_f32_e32 v194, 0xbfb8aa3b, v186
	v_mul_f32_e32 v195, 0xbfb8aa3b, v187
	v_mul_f32_e32 v196, 0xbfb8aa3b, v188
	v_mul_f32_e32 v197, 0xbfb8aa3b, v189
	v_mul_f32_e32 v198, 0xbfb8aa3b, v190
	v_mul_f32_e32 v199, 0xbfb8aa3b, v191
	v_exp_f32_e32 v192, v192
	v_exp_f32_e32 v193, v193
	v_exp_f32_e32 v194, v194
	v_exp_f32_e32 v195, v195
	v_exp_f32_e32 v196, v196
	v_exp_f32_e32 v197, v197
	v_exp_f32_e32 v198, v198
	v_exp_f32_e32 v199, v199
	v_add_f32_e32 v192, 1.0, v192
	v_add_f32_e32 v193, 1.0, v193
	v_add_f32_e32 v194, 1.0, v194
	v_add_f32_e32 v195, 1.0, v195
	v_add_f32_e32 v196, 1.0, v196
	v_add_f32_e32 v197, 1.0, v197
	v_add_f32_e32 v198, 1.0, v198
	v_add_f32_e32 v199, 1.0, v199
	v_rcp_f32_e32 v192, v192
	v_rcp_f32_e32 v193, v193
	v_rcp_f32_e32 v194, v194
	v_rcp_f32_e32 v195, v195
	v_rcp_f32_e32 v196, v196
	v_rcp_f32_e32 v197, v197
	v_rcp_f32_e32 v198, v198
	v_rcp_f32_e32 v199, v199
	v_mul_f32_e32 v184, v184, v192
	v_mul_f32_e32 v185, v185, v193
	v_mul_f32_e32 v186, v186, v194
	v_mul_f32_e32 v187, v187, v195
	v_mul_f32_e32 v188, v188, v196
	v_mul_f32_e32 v189, v189, v197
	v_mul_f32_e32 v190, v190, v198
	v_mul_f32_e32 v191, v191, v199
	v_mul_f32_e32 v184, v158, v184
	v_mul_f32_e32 v185, v159, v185
	v_mul_f32_e32 v186, v160, v186
	v_mul_f32_e32 v187, v161, v187
	v_mul_f32_e32 v188, v154, v188
	v_mul_f32_e32 v189, v155, v189
	v_mul_f32_e32 v190, v156, v190
	v_mul_f32_e32 v191, v157, v191
	v_cvt_pk_bf16_f32 v200, v184, v185
	v_cvt_pk_bf16_f32 v201, v186, v187
	v_cvt_pk_bf16_f32 v202, v188, v189
	v_cvt_pk_bf16_f32 v203, v190, v191
	s_lshr_b32 s10, s55, 6
	s_mul_i32 s10, s10, 0x5800
	s_add_u32 s94, s62, s10
	s_addc_u32 s95, s63, 0
	s_mov_b64 exec, s[4:5]
	global_store_dwordx4 v183, v[200:203], s[92:93]
	s_mov_b64 exec, s[6:7]
	v_cvt_pk_bf16_f32 v228, v150, v151
	v_cvt_pk_bf16_f32 v229, v152, v153
	v_cvt_pk_bf16_f32 v230, v142, v143
	v_cvt_pk_bf16_f32 v231, v144, v145
	v_cvt_pk_bf16_f32 v232, v158, v159
	v_cvt_pk_bf16_f32 v233, v160, v161
	v_cvt_pk_bf16_f32 v234, v154, v155
	v_cvt_pk_bf16_f32 v235, v156, v157
	global_store_dwordx4 v236, v[228:231], s[94:95]
	global_store_dwordx4 v237, v[232:235], s[94:95]
	s_mov_b64 exec, -1
	s_cmpk_lg_i32 s32, 0x800
	s_cbranch_scc1 .Lp8e_noout_00
	s_mul_i32 s10, s83, 0x5800
	s_add_u32 s94, s72, s10
	s_addc_u32 s95, s73, 0
	s_mov_b64 exec, s[8:9]
	global_store_dwordx4 v239, v[150:153], s[94:95]
	global_store_dwordx4 v239, v[142:145], s[94:95] offset:16
	s_mov_b64 exec, -1
; __device__ __forceinline__ u32x4 pack8(const float (&f)[8]) { u32x4 o; o.x = cvt_pk_bf16(f[0], f[1]); o.y = cvt_pk_bf16(f[2], f[3]); o.z = cvt_pk_bf16(f[4], f[5]); o.w = cvt_pk_bf16(f[6], f[7]); return o; }
; __device__ __forceinline__ float sigmoidf_(float x) { return __builtin_amdgcn_rcpf(1.0f + __expf(-x)); }
; __device__ __forceinline__ float dpp_ror1(float x) { return __builtin_bit_cast(float, __builtin_amdgcn_update_dpp(0, __builtin_bit_cast(int, x), 0x121, 0xf, 0xf, false)); }
; __device__ __forceinline__ float dpp_ror2(float x) { return __builtin_bit_cast(float, __builtin_amdgcn_update_dpp(0, __builtin_bit_cast(int, x), 0x122, 0xf, 0xf, false)); }
;     __device__ __forceinline__ void operator()(const f32x4 (&acc)[2][2][4][2], const Unit& u, int wr, int wc, int fr, int fq) const {
;     ...
;                 for (int m = 0; m < 4; ++m) { const int r = rbase + ai * HALF + 16 * m; const bool hi = r >= rb; const int t = hi ? r - rb : r - b0 * TP, b = hi ? b0 + 1 : b0;
;                     float o[8], uu[8], gg[8];
; #pragma unroll
;                     for (int k = 0; k < 8; ++k) { const float x = acc[ai][0][m][k >> 2][k & 3], g = acc[ai][1][m][k >> 2][k & 3]; uu[k] = x; gg[k] = g;
;                         float u1 = dpp_ror1(x), u2 = dpp_ror2(x);
;                         if (m > 0) { const float xp = acc[ai][0][m > 0 ? m - 1 : 0][k >> 2][k & 3]; const float p1 = dpp_ror1(xp), p2 = dpp_ror2(xp); u1 = fr >= 1 ? u1 : p1; u2 = fr >= 2 ? u2 : p2; }
;                         if (t == 0) u1 = 0.f; if (t <= 1) u2 = 0.f;
;                         const float uc = w0[k] * u2 + w1[k] * u1 + w2[k] * x + bb[k]; o[k] = uc * sigmoidf_(uc) * g; }
;                     if (m > 0 || fr >= 2) *(u32x4*)(ACT + (size_t)r * DFF + ch0) = pack8(o);
;                     if (m == 0 && fr < 2) { const int blk = r >> 6; *(u32x4*)(EF + ((size_t)(blk * 2 + fr) * 2) * DFF + ch0) = pack8(uu); *(u32x4*)(EF + ((size_t)(blk * 2 + fr) * 2 + 1) * DFF + ch0) = pack8(gg); }
;                     if (m == 3 && fr >= 14) { const int blk = r >> 6; *(u32x4*)(EL + (size_t)(blk * 2 + (fr - 14)) * DFF + ch0) = pack8(uu); }
;                     if (t >= TP - 2) store8f(outp + ((size_t)(b * 2) + (t - (TP - 2))) * DFF + ch0, uu); }
.Lp8e_noout_00:
	s_add_i32 s55, s91, 16
	s_cmp_ge_i32 s55, s85
	s_cselect_b32 s83, s54, s35
	s_mul_i32 s32, s83, 0x810
	s_sub_i32 s32, s55, s32
	s_mul_i32 s10, s55, 0x1600
	s_add_u32 s92, s60, s10
	s_addc_u32 s93, s61, 0
	v_fma_f32 v184, v66, v134, v74
	v_fma_f32 v185, v67, v135, v75
	v_fma_f32 v186, v68, v136, v76
	v_fma_f32 v187, v69, v137, v77
	v_fma_f32 v188, v70, v126, v78
	v_fma_f32 v189, v71, v127, v79
	v_fma_f32 v190, v72, v128, v80
	v_fma_f32 v191, v73, v129, v81
	v_fmac_f32_dpp v184, v134, v58 row_shr:1 row_mask:0xf bank_mask:0xf
	v_fmac_f32_dpp v185, v135, v59 row_shr:1 row_mask:0xf bank_mask:0xf
	v_fmac_f32_dpp v186, v136, v60 row_shr:1 row_mask:0xf bank_mask:0xf
	v_fmac_f32_dpp v187, v137, v61 row_shr:1 row_mask:0xf bank_mask:0xf
	v_fmac_f32_dpp v188, v126, v62 row_shr:1 row_mask:0xf bank_mask:0xf
	v_fmac_f32_dpp v189, v127, v63 row_shr:1 row_mask:0xf bank_mask:0xf
	v_fmac_f32_dpp v190, v128, v64 row_shr:1 row_mask:0xf bank_mask:0xf
	v_fmac_f32_dpp v191, v129, v65 row_shr:1 row_mask:0xf bank_mask:0xf
	v_fmac_f32_dpp v184, v134, v50 row_shr:2 row_mask:0xf bank_mask:0xf
	v_fmac_f32_dpp v185, v135, v51 row_shr:2 row_mask:0xf bank_mask:0xf
	v_fmac_f32_dpp v186, v136, v52 row_shr:2 row_mask:0xf bank_mask:0xf
	v_fmac_f32_dpp v187, v137, v53 row_shr:2 row_mask:0xf bank_mask:0xf
	v_fmac_f32_dpp v188, v126, v54 row_shr:2 row_mask:0xf bank_mask:0xf
	v_fmac_f32_dpp v189, v127, v55 row_shr:2 row_mask:0xf bank_mask:0xf
	v_fmac_f32_dpp v190, v128, v56 row_shr:2 row_mask:0xf bank_mask:0xf
	v_fmac_f32_dpp v191, v129, v57 row_shr:2 row_mask:0xf bank_mask:0xf
	s_cmp_eq_u32 s32, 0
	s_cbranch_scc1 .Lp8e_nohalo_01
	v_fmac_f32_dpp v184, v150, v58 row_shl:15 row_mask:0xf bank_mask:0xf
	v_fmac_f32_dpp v185, v151, v59 row_shl:15 row_mask:0xf bank_mask:0xf
	v_fmac_f32_dpp v186, v152, v60 row_shl:15 row_mask:0xf bank_mask:0xf
	v_fmac_f32_dpp v187, v153, v61 row_shl:15 row_mask:0xf bank_mask:0xf
	v_fmac_f32_dpp v188, v142, v62 row_shl:15 row_mask:0xf bank_mask:0xf
	v_fmac_f32_dpp v189, v143, v63 row_shl:15 row_mask:0xf bank_mask:0xf
	v_fmac_f32_dpp v190, v144, v64 row_shl:15 row_mask:0xf bank_mask:0xf
	v_fmac_f32_dpp v191, v145, v65 row_shl:15 row_mask:0xf bank_mask:0xf
	v_fmac_f32_dpp v184, v150, v50 row_shl:14 row_mask:0xf bank_mask:0xf
	v_fmac_f32_dpp v185, v151, v51 row_shl:14 row_mask:0xf bank_mask:0xf
	v_fmac_f32_dpp v186, v152, v52 row_shl:14 row_mask:0xf bank_mask:0xf
	v_fmac_f32_dpp v187, v153, v53 row_shl:14 row_mask:0xf bank_mask:0xf
	v_fmac_f32_dpp v188, v142, v54 row_shl:14 row_mask:0xf bank_mask:0xf
	v_fmac_f32_dpp v189, v143, v55 row_shl:14 row_mask:0xf bank_mask:0xf
	v_fmac_f32_dpp v190, v144, v56 row_shl:14 row_mask:0xf bank_mask:0xf
	v_fmac_f32_dpp v191, v145, v57 row_shl:14 row_mask:0xf bank_mask:0xf
.Lp8e_nohalo_01:
	v_mul_f32_e32 v192, 0xbfb8aa3b, v184
	v_mul_f32_e32 v193, 0xbfb8aa3b, v185
	v_mul_f32_e32 v194, 0xbfb8aa3b, v186
	v_mul_f32_e32 v195, 0xbfb8aa3b, v187
	v_mul_f32_e32 v196, 0xbfb8aa3b, v188
	v_mul_f32_e32 v197, 0xbfb8aa3b, v189
	v_mul_f32_e32 v198, 0xbfb8aa3b, v190
	v_mul_f32_e32 v199, 0xbfb8aa3b, v191
	v_exp_f32_e32 v192, v192
	v_exp_f32_e32 v193, v193
	v_exp_f32_e32 v194, v194
	v_exp_f32_e32 v195, v195
	v_exp_f32_e32 v196, v196
	v_exp_f32_e32 v197, v197
	v_exp_f32_e32 v198, v198
	v_exp_f32_e32 v199, v199
	v_add_f32_e32 v192, 1.0, v192
	v_add_f32_e32 v193, 1.0, v193
	v_add_f32_e32 v194, 1.0, v194
	v_add_f32_e32 v195, 1.0, v195
	v_add_f32_e32 v196, 1.0, v196
	v_add_f32_e32 v197, 1.0, v197
	v_add_f32_e32 v198, 1.0, v198
	v_add_f32_e32 v199, 1.0, v199
	v_rcp_f32_e32 v192, v192
	v_rcp_f32_e32 v193, v193
	v_rcp_f32_e32 v194, v194
	v_rcp_f32_e32 v195, v195
	v_rcp_f32_e32 v196, v196
	v_rcp_f32_e32 v197, v197
	v_rcp_f32_e32 v198, v198
	v_rcp_f32_e32 v199, v199
	v_mul_f32_e32 v184, v184, v192
	v_mul_f32_e32 v185, v185, v193
	v_mul_f32_e32 v186, v186, v194
	v_mul_f32_e32 v187, v187, v195
	v_mul_f32_e32 v188, v188, v196
	v_mul_f32_e32 v189, v189, v197
	v_mul_f32_e32 v190, v190, v198
	v_mul_f32_e32 v191, v191, v199
	v_mul_f32_e32 v184, v146, v184
	v_mul_f32_e32 v185, v147, v185
	v_mul_f32_e32 v186, v148, v186
	v_mul_f32_e32 v187, v149, v187
	v_mul_f32_e32 v188, v138, v188
	v_mul_f32_e32 v189, v139, v189
	v_mul_f32_e32 v190, v140, v190
	v_mul_f32_e32 v191, v141, v191
	v_cvt_pk_bf16_f32 v224, v184, v185
	v_cvt_pk_bf16_f32 v225, v186, v187
	v_cvt_pk_bf16_f32 v226, v188, v189
	v_cvt_pk_bf16_f32 v227, v190, v191
	global_store_dwordx4 v183, v[224:227], s[92:93]
	s_cmpk_lg_i32 s32, 0x800
	s_cbranch_scc1 .Lp8e_noout_01
	s_mul_i32 s10, s83, 0x5800
	s_add_u32 s94, s72, s10
	s_addc_u32 s95, s73, 0
	s_mov_b64 exec, s[8:9]
	global_store_dwordx4 v239, v[134:137], s[94:95]
	global_store_dwordx4 v239, v[126:129], s[94:95] offset:16
	s_mov_b64 exec, -1
; __device__ __forceinline__ u32x4 pack8(const float (&f)[8]) { u32x4 o; o.x = cvt_pk_bf16(f[0], f[1]); o.y = cvt_pk_bf16(f[2], f[3]); o.z = cvt_pk_bf16(f[4], f[5]); o.w = cvt_pk_bf16(f[6], f[7]); return o; }
; __device__ __forceinline__ float sigmoidf_(float x) { return __builtin_amdgcn_rcpf(1.0f + __expf(-x)); }
; __device__ __forceinline__ float dpp_ror1(float x) { return __builtin_bit_cast(float, __builtin_amdgcn_update_dpp(0, __builtin_bit_cast(int, x), 0x121, 0xf, 0xf, false)); }
; __device__ __forceinline__ float dpp_ror2(float x) { return __builtin_bit_cast(float, __builtin_amdgcn_update_dpp(0, __builtin_bit_cast(int, x), 0x122, 0xf, 0xf, false)); }
;     __device__ __forceinline__ void operator()(const f32x4 (&acc)[2][2][4][2], const Unit& u, int wr, int wc, int fr, int fq) const {
;     ...
;                 for (int m = 0; m < 4; ++m) { const int r = rbase + ai * HALF + 16 * m; const bool hi = r >= rb; const int t = hi ? r - rb : r - b0 * TP, b = hi ? b0 + 1 : b0;
;                     float o[8], uu[8], gg[8];
; #pragma unroll
;                     for (int k = 0; k < 8; ++k) { const float x = acc[ai][0][m][k >> 2][k & 3], g = acc[ai][1][m][k >> 2][k & 3]; uu[k] = x; gg[k] = g;
;                         float u1 = dpp_ror1(x), u2 = dpp_ror2(x);
;                         if (m > 0) { const float xp = acc[ai][0][m > 0 ? m - 1 : 0][k >> 2][k & 3]; const float p1 = dpp_ror1(xp), p2 = dpp_ror2(xp); u1 = fr >= 1 ? u1 : p1; u2 = fr >= 2 ? u2 : p2; }
;                         if (t == 0) u1 = 0.f; if (t <= 1) u2 = 0.f;
;                         const float uc = w0[k] * u2 + w1[k] * u1 + w2[k] * x + bb[k]; o[k] = uc * sigmoidf_(uc) * g; }
;                     if (m > 0 || fr >= 2) *(u32x4*)(ACT + (size_t)r * DFF + ch0) = pack8(o);
;                     if (m == 0 && fr < 2) { const int blk = r >> 6; *(u32x4*)(EF + ((size_t)(blk * 2 + fr) * 2) * DFF + ch0) = pack8(uu); *(u32x4*)(EF + ((size_t)(blk * 2 + fr) * 2 + 1) * DFF + ch0) = pack8(gg); }
;                     if (m == 3 && fr >= 14) { const int blk = r >> 6; *(u32x4*)(EL + (size_t)(blk * 2 + (fr - 14)) * DFF + ch0) = pack8(uu); }
;                     if (t >= TP - 2) store8f(outp + ((size_t)(b * 2) + (t - (TP - 2))) * DFF + ch0, uu); }
.Lp8e_noout_01:
	s_add_i32 s55, s91, 32
	s_cmp_ge_i32 s55, s85
	s_cselect_b32 s83, s54, s35
	s_mul_i32 s32, s83, 0x810
	s_sub_i32 s32, s55, s32
	s_mul_i32 s10, s55, 0x1600
	s_add_u32 s92, s60, s10
	s_addc_u32 s93, s61, 0
	v_fma_f32 v184, v66, v118, v74
	v_fma_f32 v185, v67, v119, v75
	v_fma_f32 v186, v68, v120, v76
	v_fma_f32 v187, v69, v121, v77
	v_fma_f32 v188, v70, v110, v78
	v_fma_f32 v189, v71, v111, v79
	v_fma_f32 v190, v72, v112, v80
	v_fma_f32 v191, v73, v113, v81
	v_fmac_f32_dpp v184, v118, v58 row_shr:1 row_mask:0xf bank_mask:0xf
	v_fmac_f32_dpp v185, v119, v59 row_shr:1 row_mask:0xf bank_mask:0xf
	v_fmac_f32_dpp v186, v120, v60 row_shr:1 row_mask:0xf bank_mask:0xf
	v_fmac_f32_dpp v187, v121, v61 row_shr:1 row_mask:0xf bank_mask:0xf
	v_fmac_f32_dpp v188, v110, v62 row_shr:1 row_mask:0xf bank_mask:0xf
	v_fmac_f32_dpp v189, v111, v63 row_shr:1 row_mask:0xf bank_mask:0xf
	v_fmac_f32_dpp v190, v112, v64 row_shr:1 row_mask:0xf bank_mask:0xf
	v_fmac_f32_dpp v191, v113, v65 row_shr:1 row_mask:0xf bank_mask:0xf
	v_fmac_f32_dpp v184, v118, v50 row_shr:2 row_mask:0xf bank_mask:0xf
	v_fmac_f32_dpp v185, v119, v51 row_shr:2 row_mask:0xf bank_mask:0xf
	v_fmac_f32_dpp v186, v120, v52 row_shr:2 row_mask:0xf bank_mask:0xf
	v_fmac_f32_dpp v187, v121, v53 row_shr:2 row_mask:0xf bank_mask:0xf
	v_fmac_f32_dpp v188, v110, v54 row_shr:2 row_mask:0xf bank_mask:0xf
	v_fmac_f32_dpp v189, v111, v55 row_shr:2 row_mask:0xf bank_mask:0xf
	v_fmac_f32_dpp v190, v112, v56 row_shr:2 row_mask:0xf bank_mask:0xf
	v_fmac_f32_dpp v191, v113, v57 row_shr:2 row_mask:0xf bank_mask:0xf
	s_cmp_eq_u32 s32, 0
	s_cbranch_scc1 .Lp8e_nohalo_02
	v_fmac_f32_dpp v184, v134, v58 row_shl:15 row_mask:0xf bank_mask:0xf
	v_fmac_f32_dpp v185, v135, v59 row_shl:15 row_mask:0xf bank_mask:0xf
	v_fmac_f32_dpp v186, v136, v60 row_shl:15 row_mask:0xf bank_mask:0xf
	v_fmac_f32_dpp v187, v137, v61 row_shl:15 row_mask:0xf bank_mask:0xf
	v_fmac_f32_dpp v188, v126, v62 row_shl:15 row_mask:0xf bank_mask:0xf
	v_fmac_f32_dpp v189, v127, v63 row_shl:15 row_mask:0xf bank_mask:0xf
	v_fmac_f32_dpp v190, v128, v64 row_shl:15 row_mask:0xf bank_mask:0xf
	v_fmac_f32_dpp v191, v129, v65 row_shl:15 row_mask:0xf bank_mask:0xf
	v_fmac_f32_dpp v184, v134, v50 row_shl:14 row_mask:0xf bank_mask:0xf
	v_fmac_f32_dpp v185, v135, v51 row_shl:14 row_mask:0xf bank_mask:0xf
	v_fmac_f32_dpp v186, v136, v52 row_shl:14 row_mask:0xf bank_mask:0xf
	v_fmac_f32_dpp v187, v137, v53 row_shl:14 row_mask:0xf bank_mask:0xf
	v_fmac_f32_dpp v188, v126, v54 row_shl:14 row_mask:0xf bank_mask:0xf
	v_fmac_f32_dpp v189, v127, v55 row_shl:14 row_mask:0xf bank_mask:0xf
	v_fmac_f32_dpp v190, v128, v56 row_shl:14 row_mask:0xf bank_mask:0xf
	v_fmac_f32_dpp v191, v129, v57 row_shl:14 row_mask:0xf bank_mask:0xf
.Lp8e_nohalo_02:
	v_mul_f32_e32 v192, 0xbfb8aa3b, v184
	v_mul_f32_e32 v193, 0xbfb8aa3b, v185
	v_mul_f32_e32 v194, 0xbfb8aa3b, v186
	v_mul_f32_e32 v195, 0xbfb8aa3b, v187
	v_mul_f32_e32 v196, 0xbfb8aa3b, v188
	v_mul_f32_e32 v197, 0xbfb8aa3b, v189
	v_mul_f32_e32 v198, 0xbfb8aa3b, v190
	v_mul_f32_e32 v199, 0xbfb8aa3b, v191
	v_exp_f32_e32 v192, v192
	v_exp_f32_e32 v193, v193
	v_exp_f32_e32 v194, v194
	v_exp_f32_e32 v195, v195
	v_exp_f32_e32 v196, v196
	v_exp_f32_e32 v197, v197
	v_exp_f32_e32 v198, v198
	v_exp_f32_e32 v199, v199
	v_add_f32_e32 v192, 1.0, v192
	v_add_f32_e32 v193, 1.0, v193
	v_add_f32_e32 v194, 1.0, v194
	v_add_f32_e32 v195, 1.0, v195
	v_add_f32_e32 v196, 1.0, v196
	v_add_f32_e32 v197, 1.0, v197
	v_add_f32_e32 v198, 1.0, v198
	v_add_f32_e32 v199, 1.0, v199
	v_rcp_f32_e32 v192, v192
	v_rcp_f32_e32 v193, v193
	v_rcp_f32_e32 v194, v194
	v_rcp_f32_e32 v195, v195
	v_rcp_f32_e32 v196, v196
	v_rcp_f32_e32 v197, v197
	v_rcp_f32_e32 v198, v198
	v_rcp_f32_e32 v199, v199
	v_mul_f32_e32 v184, v184, v192
	v_mul_f32_e32 v185, v185, v193
	v_mul_f32_e32 v186, v186, v194
	v_mul_f32_e32 v187, v187, v195
	v_mul_f32_e32 v188, v188, v196
	v_mul_f32_e32 v189, v189, v197
	v_mul_f32_e32 v190, v190, v198
	v_mul_f32_e32 v191, v191, v199
	v_mul_f32_e32 v184, v130, v184
	v_mul_f32_e32 v185, v131, v185
	v_mul_f32_e32 v186, v132, v186
	v_mul_f32_e32 v187, v133, v187
	v_mul_f32_e32 v188, v122, v188
	v_mul_f32_e32 v189, v123, v189
	v_mul_f32_e32 v190, v124, v190
	v_mul_f32_e32 v191, v125, v191
	v_cvt_pk_bf16_f32 v200, v184, v185
	v_cvt_pk_bf16_f32 v201, v186, v187
	v_cvt_pk_bf16_f32 v202, v188, v189
	v_cvt_pk_bf16_f32 v203, v190, v191
	global_store_dwordx4 v183, v[200:203], s[92:93]
	s_cmpk_lg_i32 s32, 0x800
	s_cbranch_scc1 .Lp8e_noout_02
	s_mul_i32 s10, s83, 0x5800
	s_add_u32 s94, s72, s10
	s_addc_u32 s95, s73, 0
	s_mov_b64 exec, s[8:9]
	global_store_dwordx4 v239, v[118:121], s[94:95]
	global_store_dwordx4 v239, v[110:113], s[94:95] offset:16
	s_mov_b64 exec, -1
; __device__ __forceinline__ u32x4 pack8(const float (&f)[8]) { u32x4 o; o.x = cvt_pk_bf16(f[0], f[1]); o.y = cvt_pk_bf16(f[2], f[3]); o.z = cvt_pk_bf16(f[4], f[5]); o.w = cvt_pk_bf16(f[6], f[7]); return o; }
; __device__ __forceinline__ float sigmoidf_(float x) { return __builtin_amdgcn_rcpf(1.0f + __expf(-x)); }
; __device__ __forceinline__ float dpp_ror1(float x) { return __builtin_bit_cast(float, __builtin_amdgcn_update_dpp(0, __builtin_bit_cast(int, x), 0x121, 0xf, 0xf, false)); }
; __device__ __forceinline__ float dpp_ror2(float x) { return __builtin_bit_cast(float, __builtin_amdgcn_update_dpp(0, __builtin_bit_cast(int, x), 0x122, 0xf, 0xf, false)); }
;     __device__ __forceinline__ void operator()(const f32x4 (&acc)[2][2][4][2], const Unit& u, int wr, int wc, int fr, int fq) const {
;     ...
;                 for (int m = 0; m < 4; ++m) { const int r = rbase + ai * HALF + 16 * m; const bool hi = r >= rb; const int t = hi ? r - rb : r - b0 * TP, b = hi ? b0 + 1 : b0;
;                     float o[8], uu[8], gg[8];
; #pragma unroll
;                     for (int k = 0; k < 8; ++k) { const float x = acc[ai][0][m][k >> 2][k & 3], g = acc[ai][1][m][k >> 2][k & 3]; uu[k] = x; gg[k] = g;
;                         float u1 = dpp_ror1(x), u2 = dpp_ror2(x);
;                         if (m > 0) { const float xp = acc[ai][0][m > 0 ? m - 1 : 0][k >> 2][k & 3]; const float p1 = dpp_ror1(xp), p2 = dpp_ror2(xp); u1 = fr >= 1 ? u1 : p1; u2 = fr >= 2 ? u2 : p2; }
;                         if (t == 0) u1 = 0.f; if (t <= 1) u2 = 0.f;
;                         const float uc = w0[k] * u2 + w1[k] * u1 + w2[k] * x + bb[k]; o[k] = uc * sigmoidf_(uc) * g; }
;                     if (m > 0 || fr >= 2) *(u32x4*)(ACT + (size_t)r * DFF + ch0) = pack8(o);
;                     if (m == 0 && fr < 2) { const int blk = r >> 6; *(u32x4*)(EF + ((size_t)(blk * 2 + fr) * 2) * DFF + ch0) = pack8(uu); *(u32x4*)(EF + ((size_t)(blk * 2 + fr) * 2 + 1) * DFF + ch0) = pack8(gg); }
;                     if (m == 3 && fr >= 14) { const int blk = r >> 6; *(u32x4*)(EL + (size_t)(blk * 2 + (fr - 14)) * DFF + ch0) = pack8(uu); }
;                     if (t >= TP - 2) store8f(outp + ((size_t)(b * 2) + (t - (TP - 2))) * DFF + ch0, uu); }
.Lp8e_noout_02:
	s_add_i32 s55, s91, 48
	s_cmp_ge_i32 s55, s85
	s_cselect_b32 s83, s54, s35
	s_mul_i32 s32, s83, 0x810
	s_sub_i32 s32, s55, s32
	s_mul_i32 s10, s55, 0x1600
	s_add_u32 s92, s60, s10
	s_addc_u32 s93, s61, 0
	v_fma_f32 v184, v66, v102, v74
	v_fma_f32 v185, v67, v103, v75
	v_fma_f32 v186, v68, v104, v76
	v_fma_f32 v187, v69, v105, v77
	v_fma_f32 v188, v70, v98, v78
	v_fma_f32 v189, v71, v99, v79
	v_fma_f32 v190, v72, v100, v80
	v_fma_f32 v191, v73, v101, v81
	v_fmac_f32_dpp v184, v102, v58 row_shr:1 row_mask:0xf bank_mask:0xf
	v_fmac_f32_dpp v185, v103, v59 row_shr:1 row_mask:0xf bank_mask:0xf
	v_fmac_f32_dpp v186, v104, v60 row_shr:1 row_mask:0xf bank_mask:0xf
	v_fmac_f32_dpp v187, v105, v61 row_shr:1 row_mask:0xf bank_mask:0xf
	v_fmac_f32_dpp v188, v98, v62 row_shr:1 row_mask:0xf bank_mask:0xf
	v_fmac_f32_dpp v189, v99, v63 row_shr:1 row_mask:0xf bank_mask:0xf
	v_fmac_f32_dpp v190, v100, v64 row_shr:1 row_mask:0xf bank_mask:0xf
	v_fmac_f32_dpp v191, v101, v65 row_shr:1 row_mask:0xf bank_mask:0xf
	v_fmac_f32_dpp v184, v102, v50 row_shr:2 row_mask:0xf bank_mask:0xf
	v_fmac_f32_dpp v185, v103, v51 row_shr:2 row_mask:0xf bank_mask:0xf
	v_fmac_f32_dpp v186, v104, v52 row_shr:2 row_mask:0xf bank_mask:0xf
	v_fmac_f32_dpp v187, v105, v53 row_shr:2 row_mask:0xf bank_mask:0xf
	v_fmac_f32_dpp v188, v98, v54 row_shr:2 row_mask:0xf bank_mask:0xf
	v_fmac_f32_dpp v189, v99, v55 row_shr:2 row_mask:0xf bank_mask:0xf
	v_fmac_f32_dpp v190, v100, v56 row_shr:2 row_mask:0xf bank_mask:0xf
	v_fmac_f32_dpp v191, v101, v57 row_shr:2 row_mask:0xf bank_mask:0xf
	s_cmp_eq_u32 s32, 0
	s_cbranch_scc1 .Lp8e_nohalo_03
	v_fmac_f32_dpp v184, v118, v58 row_shl:15 row_mask:0xf bank_mask:0xf
	v_fmac_f32_dpp v185, v119, v59 row_shl:15 row_mask:0xf bank_mask:0xf
	v_fmac_f32_dpp v186, v120, v60 row_shl:15 row_mask:0xf bank_mask:0xf
	v_fmac_f32_dpp v187, v121, v61 row_shl:15 row_mask:0xf bank_mask:0xf
	v_fmac_f32_dpp v188, v110, v62 row_shl:15 row_mask:0xf bank_mask:0xf
	v_fmac_f32_dpp v189, v111, v63 row_shl:15 row_mask:0xf bank_mask:0xf
	v_fmac_f32_dpp v190, v112, v64 row_shl:15 row_mask:0xf bank_mask:0xf
	v_fmac_f32_dpp v191, v113, v65 row_shl:15 row_mask:0xf bank_mask:0xf
	v_fmac_f32_dpp v184, v118, v50 row_shl:14 row_mask:0xf bank_mask:0xf
	v_fmac_f32_dpp v185, v119, v51 row_shl:14 row_mask:0xf bank_mask:0xf
	v_fmac_f32_dpp v186, v120, v52 row_shl:14 row_mask:0xf bank_mask:0xf
	v_fmac_f32_dpp v187, v121, v53 row_shl:14 row_mask:0xf bank_mask:0xf
	v_fmac_f32_dpp v188, v110, v54 row_shl:14 row_mask:0xf bank_mask:0xf
	v_fmac_f32_dpp v189, v111, v55 row_shl:14 row_mask:0xf bank_mask:0xf
	v_fmac_f32_dpp v190, v112, v56 row_shl:14 row_mask:0xf bank_mask:0xf
	v_fmac_f32_dpp v191, v113, v57 row_shl:14 row_mask:0xf bank_mask:0xf
.Lp8e_nohalo_03:
	v_mul_f32_e32 v192, 0xbfb8aa3b, v184
	v_mul_f32_e32 v193, 0xbfb8aa3b, v185
	v_mul_f32_e32 v194, 0xbfb8aa3b, v186
	v_mul_f32_e32 v195, 0xbfb8aa3b, v187
	v_mul_f32_e32 v196, 0xbfb8aa3b, v188
	v_mul_f32_e32 v197, 0xbfb8aa3b, v189
	v_mul_f32_e32 v198, 0xbfb8aa3b, v190
	v_mul_f32_e32 v199, 0xbfb8aa3b, v191
	v_exp_f32_e32 v192, v192
	v_exp_f32_e32 v193, v193
	v_exp_f32_e32 v194, v194
	v_exp_f32_e32 v195, v195
	v_exp_f32_e32 v196, v196
	v_exp_f32_e32 v197, v197
	v_exp_f32_e32 v198, v198
	v_exp_f32_e32 v199, v199
	v_add_f32_e32 v192, 1.0, v192
	v_add_f32_e32 v193, 1.0, v193
	v_add_f32_e32 v194, 1.0, v194
	v_add_f32_e32 v195, 1.0, v195
	v_add_f32_e32 v196, 1.0, v196
	v_add_f32_e32 v197, 1.0, v197
	v_add_f32_e32 v198, 1.0, v198
	v_add_f32_e32 v199, 1.0, v199
	v_rcp_f32_e32 v192, v192
	v_rcp_f32_e32 v193, v193
	v_rcp_f32_e32 v194, v194
	v_rcp_f32_e32 v195, v195
	v_rcp_f32_e32 v196, v196
	v_rcp_f32_e32 v197, v197
	v_rcp_f32_e32 v198, v198
	v_rcp_f32_e32 v199, v199
	v_mul_f32_e32 v184, v184, v192
	v_mul_f32_e32 v185, v185, v193
	v_mul_f32_e32 v186, v186, v194
	v_mul_f32_e32 v187, v187, v195
	v_mul_f32_e32 v188, v188, v196
	v_mul_f32_e32 v189, v189, v197
	v_mul_f32_e32 v190, v190, v198
	v_mul_f32_e32 v191, v191, v199
	v_mul_f32_e32 v184, v114, v184
	v_mul_f32_e32 v185, v115, v185
	v_mul_f32_e32 v186, v116, v186
	v_mul_f32_e32 v187, v117, v187
	v_mul_f32_e32 v188, v106, v188
	v_mul_f32_e32 v189, v107, v189
	v_mul_f32_e32 v190, v108, v190
	v_mul_f32_e32 v191, v109, v191
	v_cvt_pk_bf16_f32 v224, v184, v185
	v_cvt_pk_bf16_f32 v225, v186, v187
	v_cvt_pk_bf16_f32 v226, v188, v189
	v_cvt_pk_bf16_f32 v227, v190, v191
	global_store_dwordx4 v183, v[224:227], s[92:93]
	s_lshr_b32 s10, s55, 6
	s_mul_i32 s10, s10, 0x2c00
	s_add_u32 s94, s64, s10
	s_addc_u32 s95, s65, 0
	s_mov_b64 exec, s[8:9]
	v_cvt_pk_bf16_f32 v228, v102, v103
	v_cvt_pk_bf16_f32 v229, v104, v105
	v_cvt_pk_bf16_f32 v230, v98, v99
	v_cvt_pk_bf16_f32 v231, v100, v101
	global_store_dwordx4 v238, v[228:231], s[94:95]
	s_mov_b64 exec, -1
	s_cmpk_lg_i32 s32, 0x800
	s_cbranch_scc1 .Lp8e_noout_03
	s_mul_i32 s10, s83, 0x5800
	s_add_u32 s94, s72, s10
	s_addc_u32 s95, s73, 0
	s_mov_b64 exec, s[8:9]
	global_store_dwordx4 v239, v[102:105], s[94:95]
	global_store_dwordx4 v239, v[98:101], s[94:95] offset:16
	s_mov_b64 exec, -1
; __device__ __forceinline__ u32x4 pack8(const float (&f)[8]) { u32x4 o; o.x = cvt_pk_bf16(f[0], f[1]); o.y = cvt_pk_bf16(f[2], f[3]); o.z = cvt_pk_bf16(f[4], f[5]); o.w = cvt_pk_bf16(f[6], f[7]); return o; }
; __device__ __forceinline__ float sigmoidf_(float x) { return __builtin_amdgcn_rcpf(1.0f + __expf(-x)); }
; __device__ __forceinline__ float dpp_ror1(float x) { return __builtin_bit_cast(float, __builtin_amdgcn_update_dpp(0, __builtin_bit_cast(int, x), 0x121, 0xf, 0xf, false)); }
; __device__ __forceinline__ float dpp_ror2(float x) { return __builtin_bit_cast(float, __builtin_amdgcn_update_dpp(0, __builtin_bit_cast(int, x), 0x122, 0xf, 0xf, false)); }
;     __device__ __forceinline__ void operator()(const f32x4 (&acc)[2][2][4][2], const Unit& u, int wr, int wc, int fr, int fq) const {
;     ...
;                 for (int m = 0; m < 4; ++m) { const int r = rbase + ai * HALF + 16 * m; const bool hi = r >= rb; const int t = hi ? r - rb : r - b0 * TP, b = hi ? b0 + 1 : b0;
;                     float o[8], uu[8], gg[8];
; #pragma unroll
;                     for (int k = 0; k < 8; ++k) { const float x = acc[ai][0][m][k >> 2][k & 3], g = acc[ai][1][m][k >> 2][k & 3]; uu[k] = x; gg[k] = g;
;                         float u1 = dpp_ror1(x), u2 = dpp_ror2(x);
;                         if (m > 0) { const float xp = acc[ai][0][m > 0 ? m - 1 : 0][k >> 2][k & 3]; const float p1 = dpp_ror1(xp), p2 = dpp_ror2(xp); u1 = fr >= 1 ? u1 : p1; u2 = fr >= 2 ? u2 : p2; }
;                         if (t == 0) u1 = 0.f; if (t <= 1) u2 = 0.f;
;                         const float uc = w0[k] * u2 + w1[k] * u1 + w2[k] * x + bb[k]; o[k] = uc * sigmoidf_(uc) * g; }
;                     if (m > 0 || fr >= 2) *(u32x4*)(ACT + (size_t)r * DFF + ch0) = pack8(o);
;                     if (m == 0 && fr < 2) { const int blk = r >> 6; *(u32x4*)(EF + ((size_t)(blk * 2 + fr) * 2) * DFF + ch0) = pack8(uu); *(u32x4*)(EF + ((size_t)(blk * 2 + fr) * 2 + 1) * DFF + ch0) = pack8(gg); }
;                     if (m == 3 && fr >= 14) { const int blk = r >> 6; *(u32x4*)(EL + (size_t)(blk * 2 + (fr - 14)) * DFF + ch0) = pack8(uu); }
;                     if (t >= TP - 2) store8f(outp + ((size_t)(b * 2) + (t - (TP - 2))) * DFF + ch0, uu); }
.Lp8e_noout_03:
	s_add_i32 s55, s91, 128
	s_cmp_ge_i32 s55, s85
	s_cselect_b32 s83, s54, s35
	s_mul_i32 s32, s83, 0x810
	s_sub_i32 s32, s55, s32
	s_mul_i32 s10, s55, 0x1600
	s_add_u32 s92, s60, s10
	s_addc_u32 s93, s61, 0
	v_fma_f32 v184, v66, v90, v74
	v_fma_f32 v185, v67, v91, v75
	v_fma_f32 v186, v68, v92, v76
	v_fma_f32 v187, v69, v93, v77
	v_fma_f32 v188, v70, v86, v78
	v_fma_f32 v189, v71, v87, v79
	v_fma_f32 v190, v72, v88, v80
	v_fma_f32 v191, v73, v89, v81
	v_fmac_f32_dpp v184, v90, v58 row_shr:1 row_mask:0xf bank_mask:0xf
	v_fmac_f32_dpp v185, v91, v59 row_shr:1 row_mask:0xf bank_mask:0xf
	v_fmac_f32_dpp v186, v92, v60 row_shr:1 row_mask:0xf bank_mask:0xf
	v_fmac_f32_dpp v187, v93, v61 row_shr:1 row_mask:0xf bank_mask:0xf
	v_fmac_f32_dpp v188, v86, v62 row_shr:1 row_mask:0xf bank_mask:0xf
	v_fmac_f32_dpp v189, v87, v63 row_shr:1 row_mask:0xf bank_mask:0xf
	v_fmac_f32_dpp v190, v88, v64 row_shr:1 row_mask:0xf bank_mask:0xf
	v_fmac_f32_dpp v191, v89, v65 row_shr:1 row_mask:0xf bank_mask:0xf
	v_fmac_f32_dpp v184, v90, v50 row_shr:2 row_mask:0xf bank_mask:0xf
	v_fmac_f32_dpp v185, v91, v51 row_shr:2 row_mask:0xf bank_mask:0xf
	v_fmac_f32_dpp v186, v92, v52 row_shr:2 row_mask:0xf bank_mask:0xf
	v_fmac_f32_dpp v187, v93, v53 row_shr:2 row_mask:0xf bank_mask:0xf
	v_fmac_f32_dpp v188, v86, v54 row_shr:2 row_mask:0xf bank_mask:0xf
	v_fmac_f32_dpp v189, v87, v55 row_shr:2 row_mask:0xf bank_mask:0xf
	v_fmac_f32_dpp v190, v88, v56 row_shr:2 row_mask:0xf bank_mask:0xf
	v_fmac_f32_dpp v191, v89, v57 row_shr:2 row_mask:0xf bank_mask:0xf
	v_mul_f32_e32 v192, 0xbfb8aa3b, v184
	v_mul_f32_e32 v193, 0xbfb8aa3b, v185
	v_mul_f32_e32 v194, 0xbfb8aa3b, v186
	v_mul_f32_e32 v195, 0xbfb8aa3b, v187
	v_mul_f32_e32 v196, 0xbfb8aa3b, v188
	v_mul_f32_e32 v197, 0xbfb8aa3b, v189
	v_mul_f32_e32 v198, 0xbfb8aa3b, v190
	v_mul_f32_e32 v199, 0xbfb8aa3b, v191
	v_exp_f32_e32 v192, v192
	v_exp_f32_e32 v193, v193
	v_exp_f32_e32 v194, v194
	v_exp_f32_e32 v195, v195
	v_exp_f32_e32 v196, v196
	v_exp_f32_e32 v197, v197
	v_exp_f32_e32 v198, v198
	v_exp_f32_e32 v199, v199
	v_add_f32_e32 v192, 1.0, v192
	v_add_f32_e32 v193, 1.0, v193
	v_add_f32_e32 v194, 1.0, v194
	v_add_f32_e32 v195, 1.0, v195
	v_add_f32_e32 v196, 1.0, v196
	v_add_f32_e32 v197, 1.0, v197
	v_add_f32_e32 v198, 1.0, v198
	v_add_f32_e32 v199, 1.0, v199
	v_rcp_f32_e32 v192, v192
	v_rcp_f32_e32 v193, v193
	v_rcp_f32_e32 v194, v194
	v_rcp_f32_e32 v195, v195
	v_rcp_f32_e32 v196, v196
	v_rcp_f32_e32 v197, v197
	v_rcp_f32_e32 v198, v198
	v_rcp_f32_e32 v199, v199
	v_mul_f32_e32 v184, v184, v192
	v_mul_f32_e32 v185, v185, v193
	v_mul_f32_e32 v186, v186, v194
	v_mul_f32_e32 v187, v187, v195
	v_mul_f32_e32 v188, v188, v196
	v_mul_f32_e32 v189, v189, v197
	v_mul_f32_e32 v190, v190, v198
	v_mul_f32_e32 v191, v191, v199
	v_mul_f32_e32 v184, v94, v184
	v_mul_f32_e32 v185, v95, v185
	v_mul_f32_e32 v186, v96, v186
	v_mul_f32_e32 v187, v97, v187
	v_mul_f32_e32 v188, v82, v188
	v_mul_f32_e32 v189, v83, v189
	v_mul_f32_e32 v190, v84, v190
	v_mul_f32_e32 v191, v85, v191
	v_cvt_pk_bf16_f32 v200, v184, v185
	v_cvt_pk_bf16_f32 v201, v186, v187
	v_cvt_pk_bf16_f32 v202, v188, v189
	v_cvt_pk_bf16_f32 v203, v190, v191
	s_lshr_b32 s10, s55, 6
	s_mul_i32 s10, s10, 0x5800
	s_add_u32 s94, s62, s10
	s_addc_u32 s95, s63, 0
	s_mov_b64 exec, s[4:5]
	global_store_dwordx4 v183, v[200:203], s[92:93]
	s_mov_b64 exec, s[6:7]
	v_cvt_pk_bf16_f32 v228, v90, v91
	v_cvt_pk_bf16_f32 v229, v92, v93
	v_cvt_pk_bf16_f32 v230, v86, v87
	v_cvt_pk_bf16_f32 v231, v88, v89
	v_cvt_pk_bf16_f32 v232, v94, v95
	v_cvt_pk_bf16_f32 v233, v96, v97
	v_cvt_pk_bf16_f32 v234, v82, v83
	v_cvt_pk_bf16_f32 v235, v84, v85
	global_store_dwordx4 v236, v[228:231], s[94:95]
	global_store_dwordx4 v237, v[232:235], s[94:95]
	s_mov_b64 exec, -1
	s_cmpk_lg_i32 s32, 0x800
	s_cbranch_scc1 .Lp8e_noout_10
	s_mul_i32 s10, s83, 0x5800
	s_add_u32 s94, s72, s10
	s_addc_u32 s95, s73, 0
	s_mov_b64 exec, s[8:9]
	global_store_dwordx4 v239, v[90:93], s[94:95]
	global_store_dwordx4 v239, v[86:89], s[94:95] offset:16
	s_mov_b64 exec, -1
.Lp8e_noout_10:
	s_add_i32 s55, s91, 144
	s_cmp_ge_i32 s55, s85
	s_cselect_b32 s83, s54, s35
	s_mul_i32 s32, s83, 0x810
	s_sub_i32 s32, s55, s32
	s_mul_i32 s10, s55, 0x1600
	s_add_u32 s92, s60, s10
	s_addc_u32 s93, s61, 0
	v_fma_f32 v184, v66, v42, v74
	v_fma_f32 v185, v67, v43, v75
	v_fma_f32 v186, v68, v44, v76
	v_fma_f32 v187, v69, v45, v77
	v_fma_f32 v188, v70, v38, v78
	v_fma_f32 v189, v71, v39, v79
	v_fma_f32 v190, v72, v40, v80
	v_fma_f32 v191, v73, v41, v81
	v_fmac_f32_dpp v184, v42, v58 row_shr:1 row_mask:0xf bank_mask:0xf
	v_fmac_f32_dpp v185, v43, v59 row_shr:1 row_mask:0xf bank_mask:0xf
	v_fmac_f32_dpp v186, v44, v60 row_shr:1 row_mask:0xf bank_mask:0xf
	v_fmac_f32_dpp v187, v45, v61 row_shr:1 row_mask:0xf bank_mask:0xf
	v_fmac_f32_dpp v188, v38, v62 row_shr:1 row_mask:0xf bank_mask:0xf
	v_fmac_f32_dpp v189, v39, v63 row_shr:1 row_mask:0xf bank_mask:0xf
	v_fmac_f32_dpp v190, v40, v64 row_shr:1 row_mask:0xf bank_mask:0xf
	v_fmac_f32_dpp v191, v41, v65 row_shr:1 row_mask:0xf bank_mask:0xf
	v_fmac_f32_dpp v184, v42, v50 row_shr:2 row_mask:0xf bank_mask:0xf
	v_fmac_f32_dpp v185, v43, v51 row_shr:2 row_mask:0xf bank_mask:0xf
	v_fmac_f32_dpp v186, v44, v52 row_shr:2 row_mask:0xf bank_mask:0xf
	v_fmac_f32_dpp v187, v45, v53 row_shr:2 row_mask:0xf bank_mask:0xf
	v_fmac_f32_dpp v188, v38, v54 row_shr:2 row_mask:0xf bank_mask:0xf
	v_fmac_f32_dpp v189, v39, v55 row_shr:2 row_mask:0xf bank_mask:0xf
	v_fmac_f32_dpp v190, v40, v56 row_shr:2 row_mask:0xf bank_mask:0xf
	v_fmac_f32_dpp v191, v41, v57 row_shr:2 row_mask:0xf bank_mask:0xf
	s_cmp_eq_u32 s32, 0
	s_cbranch_scc1 .Lp8e_nohalo_11
	v_fmac_f32_dpp v184, v90, v58 row_shl:15 row_mask:0xf bank_mask:0xf
	v_fmac_f32_dpp v185, v91, v59 row_shl:15 row_mask:0xf bank_mask:0xf
	v_fmac_f32_dpp v186, v92, v60 row_shl:15 row_mask:0xf bank_mask:0xf
	v_fmac_f32_dpp v187, v93, v61 row_shl:15 row_mask:0xf bank_mask:0xf
	v_fmac_f32_dpp v188, v86, v62 row_shl:15 row_mask:0xf bank_mask:0xf
	v_fmac_f32_dpp v189, v87, v63 row_shl:15 row_mask:0xf bank_mask:0xf
	v_fmac_f32_dpp v190, v88, v64 row_shl:15 row_mask:0xf bank_mask:0xf
	v_fmac_f32_dpp v191, v89, v65 row_shl:15 row_mask:0xf bank_mask:0xf
	v_fmac_f32_dpp v184, v90, v50 row_shl:14 row_mask:0xf bank_mask:0xf
	v_fmac_f32_dpp v185, v91, v51 row_shl:14 row_mask:0xf bank_mask:0xf
	v_fmac_f32_dpp v186, v92, v52 row_shl:14 row_mask:0xf bank_mask:0xf
	v_fmac_f32_dpp v187, v93, v53 row_shl:14 row_mask:0xf bank_mask:0xf
	v_fmac_f32_dpp v188, v86, v54 row_shl:14 row_mask:0xf bank_mask:0xf
	v_fmac_f32_dpp v189, v87, v55 row_shl:14 row_mask:0xf bank_mask:0xf
	v_fmac_f32_dpp v190, v88, v56 row_shl:14 row_mask:0xf bank_mask:0xf
	v_fmac_f32_dpp v191, v89, v57 row_shl:14 row_mask:0xf bank_mask:0xf
; __device__ __forceinline__ u32x4 pack8(const float (&f)[8]) { u32x4 o; o.x = cvt_pk_bf16(f[0], f[1]); o.y = cvt_pk_bf16(f[2], f[3]); o.z = cvt_pk_bf16(f[4], f[5]); o.w = cvt_pk_bf16(f[6], f[7]); return o; }
; __device__ __forceinline__ float sigmoidf_(float x) { return __builtin_amdgcn_rcpf(1.0f + __expf(-x)); }
; __device__ __forceinline__ float dpp_ror1(float x) { return __builtin_bit_cast(float, __builtin_amdgcn_update_dpp(0, __builtin_bit_cast(int, x), 0x121, 0xf, 0xf, false)); }
; __device__ __forceinline__ float dpp_ror2(float x) { return __builtin_bit_cast(float, __builtin_amdgcn_update_dpp(0, __builtin_bit_cast(int, x), 0x122, 0xf, 0xf, false)); }
;     __device__ __forceinline__ void operator()(const f32x4 (&acc)[2][2][4][2], const Unit& u, int wr, int wc, int fr, int fq) const {
;     ...
;                 for (int m = 0; m < 4; ++m) { const int r = rbase + ai * HALF + 16 * m; const bool hi = r >= rb; const int t = hi ? r - rb : r - b0 * TP, b = hi ? b0 + 1 : b0;
;                     float o[8], uu[8], gg[8];
; #pragma unroll
;                     for (int k = 0; k < 8; ++k) { const float x = acc[ai][0][m][k >> 2][k & 3], g = acc[ai][1][m][k >> 2][k & 3]; uu[k] = x; gg[k] = g;
;                         float u1 = dpp_ror1(x), u2 = dpp_ror2(x);
;                         if (m > 0) { const float xp = acc[ai][0][m > 0 ? m - 1 : 0][k >> 2][k & 3]; const float p1 = dpp_ror1(xp), p2 = dpp_ror2(xp); u1 = fr >= 1 ? u1 : p1; u2 = fr >= 2 ? u2 : p2; }
;                         if (t == 0) u1 = 0.f; if (t <= 1) u2 = 0.f;
;                         const float uc = w0[k] * u2 + w1[k] * u1 + w2[k] * x + bb[k]; o[k] = uc * sigmoidf_(uc) * g; }
;                     if (m > 0 || fr >= 2) *(u32x4*)(ACT + (size_t)r * DFF + ch0) = pack8(o);
;                     if (m == 0 && fr < 2) { const int blk = r >> 6; *(u32x4*)(EF + ((size_t)(blk * 2 + fr) * 2) * DFF + ch0) = pack8(uu); *(u32x4*)(EF + ((size_t)(blk * 2 + fr) * 2 + 1) * DFF + ch0) = pack8(gg); }
;                     if (m == 3 && fr >= 14) { const int blk = r >> 6; *(u32x4*)(EL + (size_t)(blk * 2 + (fr - 14)) * DFF + ch0) = pack8(uu); }
;                     if (t >= TP - 2) store8f(outp + ((size_t)(b * 2) + (t - (TP - 2))) * DFF + ch0, uu); }
.Lp8e_nohalo_11:
	v_mul_f32_e32 v192, 0xbfb8aa3b, v184
	v_mul_f32_e32 v193, 0xbfb8aa3b, v185
	v_mul_f32_e32 v194, 0xbfb8aa3b, v186
	v_mul_f32_e32 v195, 0xbfb8aa3b, v187
	v_mul_f32_e32 v196, 0xbfb8aa3b, v188
	v_mul_f32_e32 v197, 0xbfb8aa3b, v189
	v_mul_f32_e32 v198, 0xbfb8aa3b, v190
	v_mul_f32_e32 v199, 0xbfb8aa3b, v191
	v_exp_f32_e32 v192, v192
	v_exp_f32_e32 v193, v193
	v_exp_f32_e32 v194, v194
	v_exp_f32_e32 v195, v195
	v_exp_f32_e32 v196, v196
	v_exp_f32_e32 v197, v197
	v_exp_f32_e32 v198, v198
	v_exp_f32_e32 v199, v199
	v_add_f32_e32 v192, 1.0, v192
	v_add_f32_e32 v193, 1.0, v193
	v_add_f32_e32 v194, 1.0, v194
	v_add_f32_e32 v195, 1.0, v195
	v_add_f32_e32 v196, 1.0, v196
	v_add_f32_e32 v197, 1.0, v197
	v_add_f32_e32 v198, 1.0, v198
	v_add_f32_e32 v199, 1.0, v199
	v_rcp_f32_e32 v192, v192
	v_rcp_f32_e32 v193, v193
	v_rcp_f32_e32 v194, v194
	v_rcp_f32_e32 v195, v195
	v_rcp_f32_e32 v196, v196
	v_rcp_f32_e32 v197, v197
	v_rcp_f32_e32 v198, v198
	v_rcp_f32_e32 v199, v199
	v_mul_f32_e32 v184, v184, v192
	v_mul_f32_e32 v185, v185, v193
	v_mul_f32_e32 v186, v186, v194
	v_mul_f32_e32 v187, v187, v195
	v_mul_f32_e32 v188, v188, v196
	v_mul_f32_e32 v189, v189, v197
	v_mul_f32_e32 v190, v190, v198
	v_mul_f32_e32 v191, v191, v199
	v_mul_f32_e32 v184, v46, v184
	v_mul_f32_e32 v185, v47, v185
	v_mul_f32_e32 v186, v48, v186
	v_mul_f32_e32 v187, v49, v187
	v_mul_f32_e32 v188, v34, v188
	v_mul_f32_e32 v189, v35, v189
	v_mul_f32_e32 v190, v36, v190
	v_mul_f32_e32 v191, v37, v191
	v_cvt_pk_bf16_f32 v224, v184, v185
	v_cvt_pk_bf16_f32 v225, v186, v187
	v_cvt_pk_bf16_f32 v226, v188, v189
	v_cvt_pk_bf16_f32 v227, v190, v191
	global_store_dwordx4 v183, v[224:227], s[92:93]
	s_cmpk_lg_i32 s32, 0x800
	s_cbranch_scc1 .Lp8e_noout_11
	s_mul_i32 s10, s83, 0x5800
	s_add_u32 s94, s72, s10
	s_addc_u32 s95, s73, 0
	s_mov_b64 exec, s[8:9]
	global_store_dwordx4 v239, v[42:45], s[94:95]
	global_store_dwordx4 v239, v[38:41], s[94:95] offset:16
	s_mov_b64 exec, -1
.Lp8e_noout_11:
	s_add_i32 s55, s91, 160
	s_cmp_ge_i32 s55, s85
	s_cselect_b32 s83, s54, s35
	s_mul_i32 s32, s83, 0x810
	s_sub_i32 s32, s55, s32
	s_mul_i32 s10, s55, 0x1600
	s_add_u32 s92, s60, s10
	s_addc_u32 s93, s61, 0
	v_fma_f32 v184, v66, v26, v74
	v_fma_f32 v185, v67, v27, v75
	v_fma_f32 v186, v68, v28, v76
	v_fma_f32 v187, v69, v29, v77
	v_fma_f32 v188, v70, v22, v78
	v_fma_f32 v189, v71, v23, v79
	v_fma_f32 v190, v72, v24, v80
	v_fma_f32 v191, v73, v25, v81
	v_fmac_f32_dpp v184, v26, v58 row_shr:1 row_mask:0xf bank_mask:0xf
	v_fmac_f32_dpp v185, v27, v59 row_shr:1 row_mask:0xf bank_mask:0xf
	v_fmac_f32_dpp v186, v28, v60 row_shr:1 row_mask:0xf bank_mask:0xf
	v_fmac_f32_dpp v187, v29, v61 row_shr:1 row_mask:0xf bank_mask:0xf
	v_fmac_f32_dpp v188, v22, v62 row_shr:1 row_mask:0xf bank_mask:0xf
	v_fmac_f32_dpp v189, v23, v63 row_shr:1 row_mask:0xf bank_mask:0xf
	v_fmac_f32_dpp v190, v24, v64 row_shr:1 row_mask:0xf bank_mask:0xf
	v_fmac_f32_dpp v191, v25, v65 row_shr:1 row_mask:0xf bank_mask:0xf
	v_fmac_f32_dpp v184, v26, v50 row_shr:2 row_mask:0xf bank_mask:0xf
	v_fmac_f32_dpp v185, v27, v51 row_shr:2 row_mask:0xf bank_mask:0xf
	v_fmac_f32_dpp v186, v28, v52 row_shr:2 row_mask:0xf bank_mask:0xf
	v_fmac_f32_dpp v187, v29, v53 row_shr:2 row_mask:0xf bank_mask:0xf
	v_fmac_f32_dpp v188, v22, v54 row_shr:2 row_mask:0xf bank_mask:0xf
	v_fmac_f32_dpp v189, v23, v55 row_shr:2 row_mask:0xf bank_mask:0xf
	v_fmac_f32_dpp v190, v24, v56 row_shr:2 row_mask:0xf bank_mask:0xf
	v_fmac_f32_dpp v191, v25, v57 row_shr:2 row_mask:0xf bank_mask:0xf
	s_cmp_eq_u32 s32, 0
	s_cbranch_scc1 .Lp8e_nohalo_12
	v_fmac_f32_dpp v184, v42, v58 row_shl:15 row_mask:0xf bank_mask:0xf
	v_fmac_f32_dpp v185, v43, v59 row_shl:15 row_mask:0xf bank_mask:0xf
	v_fmac_f32_dpp v186, v44, v60 row_shl:15 row_mask:0xf bank_mask:0xf
	v_fmac_f32_dpp v187, v45, v61 row_shl:15 row_mask:0xf bank_mask:0xf
	v_fmac_f32_dpp v188, v38, v62 row_shl:15 row_mask:0xf bank_mask:0xf
	v_fmac_f32_dpp v189, v39, v63 row_shl:15 row_mask:0xf bank_mask:0xf
	v_fmac_f32_dpp v190, v40, v64 row_shl:15 row_mask:0xf bank_mask:0xf
	v_fmac_f32_dpp v191, v41, v65 row_shl:15 row_mask:0xf bank_mask:0xf
	v_fmac_f32_dpp v184, v42, v50 row_shl:14 row_mask:0xf bank_mask:0xf
	v_fmac_f32_dpp v185, v43, v51 row_shl:14 row_mask:0xf bank_mask:0xf
	v_fmac_f32_dpp v186, v44, v52 row_shl:14 row_mask:0xf bank_mask:0xf
	v_fmac_f32_dpp v187, v45, v53 row_shl:14 row_mask:0xf bank_mask:0xf
	v_fmac_f32_dpp v188, v38, v54 row_shl:14 row_mask:0xf bank_mask:0xf
	v_fmac_f32_dpp v189, v39, v55 row_shl:14 row_mask:0xf bank_mask:0xf
	v_fmac_f32_dpp v190, v40, v56 row_shl:14 row_mask:0xf bank_mask:0xf
	v_fmac_f32_dpp v191, v41, v57 row_shl:14 row_mask:0xf bank_mask:0xf
; __device__ __forceinline__ u32x4 pack8(const float (&f)[8]) { u32x4 o; o.x = cvt_pk_bf16(f[0], f[1]); o.y = cvt_pk_bf16(f[2], f[3]); o.z = cvt_pk_bf16(f[4], f[5]); o.w = cvt_pk_bf16(f[6], f[7]); return o; }
; __device__ __forceinline__ float sigmoidf_(float x) { return __builtin_amdgcn_rcpf(1.0f + __expf(-x)); }
; __device__ __forceinline__ float dpp_ror1(float x) { return __builtin_bit_cast(float, __builtin_amdgcn_update_dpp(0, __builtin_bit_cast(int, x), 0x121, 0xf, 0xf, false)); }
; __device__ __forceinline__ float dpp_ror2(float x) { return __builtin_bit_cast(float, __builtin_amdgcn_update_dpp(0, __builtin_bit_cast(int, x), 0x122, 0xf, 0xf, false)); }
;     __device__ __forceinline__ void operator()(const f32x4 (&acc)[2][2][4][2], const Unit& u, int wr, int wc, int fr, int fq) const {
;     ...
;                 for (int m = 0; m < 4; ++m) { const int r = rbase + ai * HALF + 16 * m; const bool hi = r >= rb; const int t = hi ? r - rb : r - b0 * TP, b = hi ? b0 + 1 : b0;
;                     float o[8], uu[8], gg[8];
; #pragma unroll
;                     for (int k = 0; k < 8; ++k) { const float x = acc[ai][0][m][k >> 2][k & 3], g = acc[ai][1][m][k >> 2][k & 3]; uu[k] = x; gg[k] = g;
;                         float u1 = dpp_ror1(x), u2 = dpp_ror2(x);
;                         if (m > 0) { const float xp = acc[ai][0][m > 0 ? m - 1 : 0][k >> 2][k & 3]; const float p1 = dpp_ror1(xp), p2 = dpp_ror2(xp); u1 = fr >= 1 ? u1 : p1; u2 = fr >= 2 ? u2 : p2; }
;                         if (t == 0) u1 = 0.f; if (t <= 1) u2 = 0.f;
;                         const float uc = w0[k] * u2 + w1[k] * u1 + w2[k] * x + bb[k]; o[k] = uc * sigmoidf_(uc) * g; }
;                     if (m > 0 || fr >= 2) *(u32x4*)(ACT + (size_t)r * DFF + ch0) = pack8(o);
;                     if (m == 0 && fr < 2) { const int blk = r >> 6; *(u32x4*)(EF + ((size_t)(blk * 2 + fr) * 2) * DFF + ch0) = pack8(uu); *(u32x4*)(EF + ((size_t)(blk * 2 + fr) * 2 + 1) * DFF + ch0) = pack8(gg); }
;                     if (m == 3 && fr >= 14) { const int blk = r >> 6; *(u32x4*)(EL + (size_t)(blk * 2 + (fr - 14)) * DFF + ch0) = pack8(uu); }
;                     if (t >= TP - 2) store8f(outp + ((size_t)(b * 2) + (t - (TP - 2))) * DFF + ch0, uu); }
.Lp8e_nohalo_12:
	v_mul_f32_e32 v192, 0xbfb8aa3b, v184
	v_mul_f32_e32 v193, 0xbfb8aa3b, v185
	v_mul_f32_e32 v194, 0xbfb8aa3b, v186
	v_mul_f32_e32 v195, 0xbfb8aa3b, v187
	v_mul_f32_e32 v196, 0xbfb8aa3b, v188
	v_mul_f32_e32 v197, 0xbfb8aa3b, v189
	v_mul_f32_e32 v198, 0xbfb8aa3b, v190
	v_mul_f32_e32 v199, 0xbfb8aa3b, v191
	v_exp_f32_e32 v192, v192
	v_exp_f32_e32 v193, v193
	v_exp_f32_e32 v194, v194
	v_exp_f32_e32 v195, v195
	v_exp_f32_e32 v196, v196
	v_exp_f32_e32 v197, v197
	v_exp_f32_e32 v198, v198
	v_exp_f32_e32 v199, v199
	v_add_f32_e32 v192, 1.0, v192
	v_add_f32_e32 v193, 1.0, v193
	v_add_f32_e32 v194, 1.0, v194
	v_add_f32_e32 v195, 1.0, v195
	v_add_f32_e32 v196, 1.0, v196
	v_add_f32_e32 v197, 1.0, v197
	v_add_f32_e32 v198, 1.0, v198
	v_add_f32_e32 v199, 1.0, v199
	v_rcp_f32_e32 v192, v192
	v_rcp_f32_e32 v193, v193
	v_rcp_f32_e32 v194, v194
	v_rcp_f32_e32 v195, v195
	v_rcp_f32_e32 v196, v196
	v_rcp_f32_e32 v197, v197
	v_rcp_f32_e32 v198, v198
	v_rcp_f32_e32 v199, v199
	v_mul_f32_e32 v184, v184, v192
	v_mul_f32_e32 v185, v185, v193
	v_mul_f32_e32 v186, v186, v194
	v_mul_f32_e32 v187, v187, v195
	v_mul_f32_e32 v188, v188, v196
	v_mul_f32_e32 v189, v189, v197
	v_mul_f32_e32 v190, v190, v198
	v_mul_f32_e32 v191, v191, v199
	v_mul_f32_e32 v184, v30, v184
	v_mul_f32_e32 v185, v31, v185
	v_mul_f32_e32 v186, v32, v186
	v_mul_f32_e32 v187, v33, v187
	v_mul_f32_e32 v188, v18, v188
	v_mul_f32_e32 v189, v19, v189
	v_mul_f32_e32 v190, v20, v190
	v_mul_f32_e32 v191, v21, v191
	v_cvt_pk_bf16_f32 v200, v184, v185
	v_cvt_pk_bf16_f32 v201, v186, v187
	v_cvt_pk_bf16_f32 v202, v188, v189
	v_cvt_pk_bf16_f32 v203, v190, v191
	global_store_dwordx4 v183, v[200:203], s[92:93]
	s_cmpk_lg_i32 s32, 0x800
	s_cbranch_scc1 .Lp8e_noout_12
	s_mul_i32 s10, s83, 0x5800
	s_add_u32 s94, s72, s10
	s_addc_u32 s95, s73, 0
	s_mov_b64 exec, s[8:9]
	global_store_dwordx4 v239, v[26:29], s[94:95]
	global_store_dwordx4 v239, v[22:25], s[94:95] offset:16
	s_mov_b64 exec, -1
.Lp8e_noout_12:
	s_add_i32 s55, s91, 176
	s_cmp_ge_i32 s55, s85
	s_cselect_b32 s83, s54, s35
	s_mul_i32 s32, s83, 0x810
	s_sub_i32 s32, s55, s32
	s_mul_i32 s10, s55, 0x1600
	s_add_u32 s92, s60, s10
	s_addc_u32 s93, s61, 0
	v_fma_f32 v184, v66, v10, v74
	v_fma_f32 v185, v67, v11, v75
	v_fma_f32 v186, v68, v12, v76
	v_fma_f32 v187, v69, v13, v77
	v_fma_f32 v188, v70, v6, v78
	v_fma_f32 v189, v71, v7, v79
	v_fma_f32 v190, v72, v8, v80
	v_fma_f32 v191, v73, v9, v81
	v_fmac_f32_dpp v184, v10, v58 row_shr:1 row_mask:0xf bank_mask:0xf
	v_fmac_f32_dpp v185, v11, v59 row_shr:1 row_mask:0xf bank_mask:0xf
	v_fmac_f32_dpp v186, v12, v60 row_shr:1 row_mask:0xf bank_mask:0xf
	v_fmac_f32_dpp v187, v13, v61 row_shr:1 row_mask:0xf bank_mask:0xf
	v_fmac_f32_dpp v188, v6, v62 row_shr:1 row_mask:0xf bank_mask:0xf
	v_fmac_f32_dpp v189, v7, v63 row_shr:1 row_mask:0xf bank_mask:0xf
	v_fmac_f32_dpp v190, v8, v64 row_shr:1 row_mask:0xf bank_mask:0xf
	v_fmac_f32_dpp v191, v9, v65 row_shr:1 row_mask:0xf bank_mask:0xf
	v_fmac_f32_dpp v184, v10, v50 row_shr:2 row_mask:0xf bank_mask:0xf
	v_fmac_f32_dpp v185, v11, v51 row_shr:2 row_mask:0xf bank_mask:0xf
	v_fmac_f32_dpp v186, v12, v52 row_shr:2 row_mask:0xf bank_mask:0xf
	v_fmac_f32_dpp v187, v13, v53 row_shr:2 row_mask:0xf bank_mask:0xf
	v_fmac_f32_dpp v188, v6, v54 row_shr:2 row_mask:0xf bank_mask:0xf
	v_fmac_f32_dpp v189, v7, v55 row_shr:2 row_mask:0xf bank_mask:0xf
	v_fmac_f32_dpp v190, v8, v56 row_shr:2 row_mask:0xf bank_mask:0xf
	v_fmac_f32_dpp v191, v9, v57 row_shr:2 row_mask:0xf bank_mask:0xf
	s_cmp_eq_u32 s32, 0
	s_cbranch_scc1 .Lp8e_nohalo_13
	v_fmac_f32_dpp v184, v26, v58 row_shl:15 row_mask:0xf bank_mask:0xf
	v_fmac_f32_dpp v185, v27, v59 row_shl:15 row_mask:0xf bank_mask:0xf
	v_fmac_f32_dpp v186, v28, v60 row_shl:15 row_mask:0xf bank_mask:0xf
	v_fmac_f32_dpp v187, v29, v61 row_shl:15 row_mask:0xf bank_mask:0xf
	v_fmac_f32_dpp v188, v22, v62 row_shl:15 row_mask:0xf bank_mask:0xf
	v_fmac_f32_dpp v189, v23, v63 row_shl:15 row_mask:0xf bank_mask:0xf
	v_fmac_f32_dpp v190, v24, v64 row_shl:15 row_mask:0xf bank_mask:0xf
	v_fmac_f32_dpp v191, v25, v65 row_shl:15 row_mask:0xf bank_mask:0xf
	v_fmac_f32_dpp v184, v26, v50 row_shl:14 row_mask:0xf bank_mask:0xf
	v_fmac_f32_dpp v185, v27, v51 row_shl:14 row_mask:0xf bank_mask:0xf
	v_fmac_f32_dpp v186, v28, v52 row_shl:14 row_mask:0xf bank_mask:0xf
	v_fmac_f32_dpp v187, v29, v53 row_shl:14 row_mask:0xf bank_mask:0xf
	v_fmac_f32_dpp v188, v22, v54 row_shl:14 row_mask:0xf bank_mask:0xf
	v_fmac_f32_dpp v189, v23, v55 row_shl:14 row_mask:0xf bank_mask:0xf
	v_fmac_f32_dpp v190, v24, v56 row_shl:14 row_mask:0xf bank_mask:0xf
	v_fmac_f32_dpp v191, v25, v57 row_shl:14 row_mask:0xf bank_mask:0xf
.Lp8e_nohalo_13:
	v_mul_f32_e32 v192, 0xbfb8aa3b, v184
	v_mul_f32_e32 v193, 0xbfb8aa3b, v185
	v_mul_f32_e32 v194, 0xbfb8aa3b, v186
	v_mul_f32_e32 v195, 0xbfb8aa3b, v187
	v_mul_f32_e32 v196, 0xbfb8aa3b, v188
	v_mul_f32_e32 v197, 0xbfb8aa3b, v189
	v_mul_f32_e32 v198, 0xbfb8aa3b, v190
	v_mul_f32_e32 v199, 0xbfb8aa3b, v191
	v_exp_f32_e32 v192, v192
	v_exp_f32_e32 v193, v193
	v_exp_f32_e32 v194, v194
	v_exp_f32_e32 v195, v195
	v_exp_f32_e32 v196, v196
	v_exp_f32_e32 v197, v197
	v_exp_f32_e32 v198, v198
	v_exp_f32_e32 v199, v199
	v_add_f32_e32 v192, 1.0, v192
	v_add_f32_e32 v193, 1.0, v193
	v_add_f32_e32 v194, 1.0, v194
	v_add_f32_e32 v195, 1.0, v195
	v_add_f32_e32 v196, 1.0, v196
	v_add_f32_e32 v197, 1.0, v197
	v_add_f32_e32 v198, 1.0, v198
	v_add_f32_e32 v199, 1.0, v199
	v_rcp_f32_e32 v192, v192
	v_rcp_f32_e32 v193, v193
	v_rcp_f32_e32 v194, v194
	v_rcp_f32_e32 v195, v195
	v_rcp_f32_e32 v196, v196
	v_rcp_f32_e32 v197, v197
	v_rcp_f32_e32 v198, v198
	v_rcp_f32_e32 v199, v199
	v_mul_f32_e32 v184, v184, v192
	v_mul_f32_e32 v185, v185, v193
	v_mul_f32_e32 v186, v186, v194
	v_mul_f32_e32 v187, v187, v195
	v_mul_f32_e32 v188, v188, v196
	v_mul_f32_e32 v189, v189, v197
	v_mul_f32_e32 v190, v190, v198
	v_mul_f32_e32 v191, v191, v199
	v_mul_f32_e32 v184, v14, v184
	v_mul_f32_e32 v185, v15, v185
	v_mul_f32_e32 v186, v16, v186
	v_mul_f32_e32 v187, v17, v187
	v_mul_f32_e32 v188, v2, v188
	v_mul_f32_e32 v189, v3, v189
	v_mul_f32_e32 v190, v4, v190
	v_mul_f32_e32 v191, v5, v191
	v_cvt_pk_bf16_f32 v224, v184, v185
	v_cvt_pk_bf16_f32 v225, v186, v187
	v_cvt_pk_bf16_f32 v226, v188, v189
	v_cvt_pk_bf16_f32 v227, v190, v191
	global_store_dwordx4 v183, v[224:227], s[92:93]
	s_lshr_b32 s10, s55, 6
	s_mul_i32 s10, s10, 0x2c00
	s_add_u32 s94, s64, s10
	s_addc_u32 s95, s65, 0
	s_mov_b64 exec, s[8:9]
	v_cvt_pk_bf16_f32 v228, v10, v11
	v_cvt_pk_bf16_f32 v229, v12, v13
	v_cvt_pk_bf16_f32 v230, v6, v7
	v_cvt_pk_bf16_f32 v231, v8, v9
	global_store_dwordx4 v238, v[228:231], s[94:95]
	s_mov_b64 exec, -1
	s_cmpk_lg_i32 s32, 0x800
	s_cbranch_scc1 .Lp8e_noout_13
	s_mul_i32 s10, s83, 0x5800
	s_add_u32 s94, s72, s10
	s_addc_u32 s95, s73, 0
	s_mov_b64 exec, s[8:9]
	global_store_dwordx4 v239, v[10:13], s[94:95]
	global_store_dwordx4 v239, v[6:9], s[94:95] offset:16
	s_mov_b64 exec, -1
.Lp8e_noout_13:
	s_mov_b64 s[12:13], 0
	s_branch .LBB0_913
